# p7pure: P7 full-unit (pm,pn) decode changed so that the 4 workgroups of a panel (row-stat exchange partners) are all piece-first or all piece-free; same XCD per panel
# speedup vs baseline: 1.0237x; 1.0088x over previous
;     __host__ __device__ bool next(int i, Unit& u) const { return at((long)i * G + c, u); }
;     __host__ __device__ bool next(int i, Unit& u) const { if (i != 0 || c >= cnt) return false; u.pm = pm0 + c / nN; u.pn = c % nN; u.k0 = 0; u.nt = ntk; return true; }
;     __host__ __device__ bool at(long L, Unit& u) const {
;         if (L >= nwg) return false;
;         int wgid = (int)L; { const int q = nwg / NXCD, r = nwg % NXCD, xcd = wgid % NXCD, off = wgid / NXCD; wgid = (xcd < r ? xcd * (q + 1) : r * (q + 1) + (xcd - r) * q) + off; }
;         const int nig = WGM * nN, gid = wgid / nig, fm = gid * WGM, gsz = (nM - fm) < WGM ? (nM - fm) : WGM;
;         u.pm = fm + ((wgid % nig) % gsz); u.pn = (wgid % nig) / gsz; u.k0 = 0; u.nt = ntk; return true;
;     __host__ __device__ bool next(int i, Unit& u) const {
;         const long L = (long)i * so.G + so.c;
;         if (L >= npieces) return so.at(L - npieces, u);
;         const int p = (int)L, tu = p / nsplit, ks = p % nsplit, nts = so.ntk / nsplit;
;         u.pm = so.nM + tu / so.nN; u.pn = tu % so.nN; u.k0 = ks * nts; u.nt = nts; return true;
.LBB0_1036:
	s_or_b64 exec, exec, s[0:1]
	v_mov_b32_e32 v153, v175
	s_cmpk_lt_i32 s2, 0x80
	s_waitcnt lgkmcnt(0)
	s_barrier
	s_cbranch_scc1 .LBB0_1041
	s_add_u32 s16, s2, 0xffffff80
	s_addc_u32 s17, 0, -1
	v_mov_b64_e32 v[0:1], 0x100
	v_cmp_lt_u64_e32 vcc, s[16:17], v[0:1]
	s_mov_b64 s[0:1], 0
	s_mov_b64 s[14:15], 0
	s_cbranch_vccz .LBB0_1039
	v_readlane_b32 s3, v255, 14
	s_and_b32 s3, s3, 56
	s_bfe_u32 s10, s16, 0x20003
	s_bfe_u32 s98, s16, 0x10007
	s_lshl_b32 s98, s98, 2
	s_or_b32 s10, s10, s98
	s_or_b32 s12, s10, s3
	s_bfe_u32 s10, s16, 0x20005
	s_mov_b64 s[14:15], -1

;     __host__ __device__ bool next(int i, Unit& u) const { return at((long)i * G + c, u); }
;     __host__ __device__ bool next(int i, Unit& u) const { if (i != 0 || c >= cnt) return false; u.pm = pm0 + c / nN; u.pn = c % nN; u.k0 = 0; u.nt = ntk; return true; }
;     __host__ __device__ bool at(long L, Unit& u) const {
;         if (L >= nwg) return false;
;         int wgid = (int)L; { const int q = nwg / NXCD, r = nwg % NXCD, xcd = wgid % NXCD, off = wgid / NXCD; wgid = (xcd < r ? xcd * (q + 1) : r * (q + 1) + (xcd - r) * q) + off; }
;         const int nig = WGM * nN, gid = wgid / nig, fm = gid * WGM, gsz = (nM - fm) < WGM ? (nM - fm) : WGM;
;         u.pm = fm + ((wgid % nig) % gsz); u.pn = (wgid % nig) / gsz; u.k0 = 0; u.nt = ntk; return true;
;     __host__ __device__ bool next(int i, Unit& u) const {
;         const long L = (long)i * so.G + so.c;
;         if (L >= npieces) return so.at(L - npieces, u);
;         const int p = (int)L, tu = p / nsplit, ks = p % nsplit, nts = so.ntk / nsplit;
;         u.pm = so.nM + tu / so.nN; u.pn = tu % so.nN; u.k0 = ks * nts; u.nt = nts; return true;
.LBB0_1048:
	s_add_i32 s72, s11, 1
	s_mul_i32 s23, s72, s96
	s_mul_hi_i32 s13, s72, s96
	s_add_u32 s28, s23, s2
	s_addc_u32 s29, s13, s58
	v_cmp_lt_i64_e32 vcc, s[28:29], v[146:147]
	s_mov_b64 s[30:31], -1
	s_cbranch_vccnz .LBB0_1051
	s_add_u32 s34, s28, 0xffffff80
	s_addc_u32 s35, s29, -1
	v_cmp_gt_u64_e32 vcc, s[34:35], v[148:149]
	s_mov_b64 s[30:31], 0
	s_mov_b64 s[40:41], 0
	s_cbranch_vccnz .LBB0_1051
	s_lshl_b32 s13, s28, 3
	s_and_b32 s13, s13, 56
	s_bfe_u32 s22, s34, 0x20003
	s_bfe_u32 s98, s34, 0x10007
	s_lshl_b32 s98, s98, 2
	s_or_b32 s22, s22, s98
	s_or_b32 s22, s22, s13
	s_bfe_u32 s24, s34, 0x20005
	s_mov_b32 s71, 64
	s_mov_b32 s26, 0
	s_mov_b64 s[40:41], -1
